# P0: workgroups 0..3 (one extra w_in transpose item per wave) skip the DT table generation; the other 252 workgroups cover it
# baseline (speedup 1.0000x reference)
; __device__ __forceinline__ unsigned pk2(float lo, float hi) { return pk2hw(lo, hi); }
; __global__ void __launch_bounds__(NTHR, 2) fwd_kernel(Args a) {
;     ...
;         for (int gi = gtid; gi < 2048 * 512; gi += NT) {
;             const int k1 = gi >> 9, j0 = (gi & 511) * 8; float v[8];
; #pragma unroll
;             for (int e = 0; e < 8; ++e) { const int j = j0 + e; const int ph = (k1 * (j & 2047)) & 2047; const float x = (float)ph * (1.0f / 1024.0f); v[e] = j < 2048 ? cospif(x) : -sinpif(x); }
;             u32x4 o; o.x = pk2(v[0], v[1]); o.y = pk2(v[2], v[3]); o.z = pk2(v[4], v[5]); o.w = pk2(v[6], v[7]);
;             *(u32x4*)(DT + (size_t)k1 * 4096 + j0) = o;
;         }
.LBB0_27:
	s_or_b64 exec, exec, s[2:3]
	s_add_u32 s72, s66, 0x7400000
	s_mov_b32 s1, 0x100000
	s_addc_u32 s73, s67, 0
	v_cmp_gt_i32_e32 vcc, s1, v4
	s_and_saveexec_b64 s[6:7], vcc
	s_cbranch_execz .LBB0_62
	v_lshl_add_u32 v5, s88, 12, v10
	s_lshl_b32 s1, s86, 12
	s_cmp_lt_u32 s88, 4
	s_cbranch_scc1 .LBB0_62
	s_sub_u32 s98, s0, 0x800
	s_sub_u32 s99, s1, 0x4000
	v_add_u32_e32 v5, 0xffffc000, v5
	s_mov_b64 s[8:9], 0
	s_movk_i32 s14, 0x7ff
	s_mov_b32 s15, 0x7f800000
	v_mov_b32_e32 v6, 0xbf1f24be
	v_mov_b32_e32 v7, 0x3e642e9d
	s_brev_b32 s16, 1
	v_mov_b32_e32 v1, 0
	s_mov_b32 s17, 0x7ffff
	v_mov_b32_e32 v8, 0xffc00000
	v_mov_b32_e32 v9, 0x7fc00000
	v_add_u32_e32 v11, 0xfffff800, v4
	s_branch .LBB0_30
.LBB0_29:
	s_or_b64 exec, exec, s[4:5]
	v_cvt_pk_bf16_f32 v12, v3, v12
	v_ashrrev_i32_e32 v3, 31, v2
	v_lshlrev_b64 v[2:3], 13, v[2:3]
	v_add_u32_e32 v11, s98, v11
	v_lshl_add_u64 v[2:3], s[72:73], 0, v[2:3]
	v_lshlrev_b32_e32 v0, 1, v0
	v_cmp_lt_i32_e32 vcc, s17, v11
	v_cvt_pk_bf16_f32 v13, v13, v14
	v_cvt_pk_bf16_f32 v14, v15, v16
	v_cvt_pk_bf16_f32 v15, v17, v22
	v_lshl_add_u64 v[2:3], v[2:3], 0, v[0:1]
	s_or_b64 s[8:9], vcc, s[8:9]
	v_add_u32_e32 v5, s99, v5
	global_store_dwordx4 v[2:3], v[12:15], off sc1
	s_andn2_b64 exec, exec, s[8:9]
	s_cbranch_execz .LBB0_62
